# MLA attention loops: K/V prefetch loads with scalar base + per-lane 32-bit offset; per-tile address VALU (2 x 64-bit add, 3 add/addc pairs) replaced by SALU
# baseline (speedup 1.0000x reference)
.LBB0_1198:
	s_abs_i32 s8, s51
	s_mul_hi_u32 s9, s8, s30
	s_mul_i32 s10, s9, s29
	s_ashr_i32 s2, s51, 31
	s_sub_i32 s8, s8, s10
	s_xor_b32 s2, s2, s26
	s_add_i32 s10, s9, 1
	s_sub_i32 s11, s8, s29
	s_cmp_ge_u32 s8, s29
	s_cselect_b32 s9, s10, s9
	s_cselect_b32 s8, s11, s8
	s_add_i32 s10, s9, 1
	s_cmp_ge_u32 s8, s29
	s_cselect_b32 s8, s10, s9
	s_xor_b32 s8, s8, s2
	s_sub_i32 s2, s8, s2
	s_mul_i32 s8, s2, s42
	s_sub_i32 s24, s51, s8
	s_ashr_i32 s25, s24, 31
	s_lshr_b32 s8, s25, 26
	s_add_i32 s8, s24, s8
	s_ashr_i32 s9, s8, 6
	s_and_b32 s10, s8, 0xffffffc0
	s_not_b32 s52, s9
	s_sub_i32 s8, s24, s10
	s_and_b32 s11, s2, 1
	s_add_i32 s52, s27, s52
	s_cmp_eq_u32 s11, 0
	s_cselect_b32 s9, s9, s52
	s_mul_i32 s2, s2, s27
	s_add_i32 s9, s9, s2
	s_lshl_b32 s2, s9, 8
	s_sub_i32 s11, s28, s2
	s_add_i32 s52, s11, 0xf00
	s_ashr_i32 s9, s8, 31
	s_mul_i32 s58, s8, 0x180000
	s_mul_hi_i32 s53, s8, 0x180000
	s_add_u32 s54, s4, s58
	s_addc_u32 s55, s5, s53
	v_or_b32_e32 v1, s52, v179
	v_mov_b64_e32 v[2:3], s[54:55]
	v_mad_i64_i32 v[2:3], s[54:55], v1, s31, v[2:3]
	v_lshl_add_u64 v[2:3], v[2:3], 0, v[166:167]
	v_mov_b32_e32 v1, v178
	global_load_dwordx4 v[118:121], v[2:3], off
	global_load_dwordx4 v[122:125], v[2:3], off offset:32
	global_load_dwordx4 v[126:129], v[2:3], off offset:64
	global_load_dwordx4 v[130:133], v[2:3], off offset:96
	global_load_dwordx4 v[134:137], v[2:3], off offset:128
	global_load_dwordx4 v[138:141], v[2:3], off offset:160
	global_load_dwordx4 v[142:145], v[2:3], off offset:192
	global_load_dwordx4 v[146:149], v[2:3], off offset:224
	global_load_dwordx4 v[150:153], v[2:3], off offset:256
	global_load_dwordx4 v[154:157], v[2:3], off offset:288
	global_load_dwordx4 v[158:161], v[2:3], off offset:320
	global_load_dwordx4 v[162:165], v[2:3], off offset:352
	s_lshl_b64 s[56:57], s[8:9], 20
	v_add_u32_e32 v185, s70, v1
	v_ashrrev_i32_e32 v4, 31, v185
	v_lshrrev_b32_e32 v4, 28, v4
	s_add_u32 s54, s6, s58
	v_lshlrev_b32_e32 v168, 3, v185
	v_add_u32_e32 v5, v185, v4
	s_addc_u32 s55, s7, s53
	v_ashrrev_i32_e32 v169, 31, v168
	v_ashrrev_i32_e32 v4, 4, v5
	v_and_b32_e32 v5, 0x1ffffff0, v5
	v_lshl_add_u64 v[2:3], v[168:169], 1, s[54:55]
	v_sub_u32_e32 v5, v185, v5
	s_add_u32 s56, s12, s56
	v_lshlrev_b32_e32 v170, 3, v5
	v_ashrrev_i32_e32 v5, 31, v4
	v_add_co_u32_e32 v8, vcc, s34, v2
	s_addc_u32 s57, s13, s57
	v_lshlrev_b64 v[172:173], 8, v[4:5]
	v_addc_co_u32_e32 v9, vcc, 0, v3, vcc
	v_lshl_add_u64 v[6:7], s[56:57], 0, v[172:173]
	v_ashrrev_i32_e32 v171, 31, v170
	global_load_dwordx4 v[98:101], v[2:3], off
	v_add_co_u32_e32 v2, vcc, s35, v2
	v_lshl_add_u64 v[6:7], v[170:171], 1, v[6:7]
	s_nop 0
	v_addc_co_u32_e32 v3, vcc, 0, v3, vcc
	global_load_dwordx4 v[102:105], v[8:9], off
	global_load_dwordx4 v[106:109], v[2:3], off
	global_load_dwordx4 v[110:113], v[6:7], off
	v_add_co_u32_e32 v2, vcc, s34, v6
	s_sub_i32 s2, 0x103f, s2
	s_nop 0
	v_addc_co_u32_e32 v3, vcc, 0, v7, vcc
	global_load_dwordx4 v[114:117], v[2:3], off
	s_ashr_i32 s9, s2, 31
	s_lshr_b32 s9, s9, 26
	s_add_i32 s2, s2, s9
	s_ashr_i32 s9, s2, 6
	s_add_i32 s2, s11, 0xf1f
	s_ashr_i32 s11, s2, 31
	s_lshr_b32 s11, s11, 26
	s_add_i32 s2, s2, s11
	s_ashr_i32 s2, s2, 6
	s_add_i32 s2, s2, 1
	s_min_i32 s2, s2, s9
	v_mul_hi_i32 v2, v185, s36
	v_add_u32_e32 v188, 0x200, v185
	v_add_u32_e32 v187, 0x400, v185
	s_cmp_lt_i32 s2, 1
	v_mul_lo_u32 v183, v4, s39
	s_mul_hi_i32 s53, s10, 0x180000
	s_mul_i32 s54, s10, 0x180000
	v_lshrrev_b32_e32 v191, 31, v2
	v_ashrrev_i32_e32 v192, 2, v2
	v_mul_hi_i32 v190, v188, s36
	v_mul_hi_i32 v189, v187, s36
	v_lshlrev_b32_e32 v184, 1, v170
	s_waitcnt vmcnt(63) expcnt(7) lgkmcnt(15)
	s_barrier
	s_cbranch_scc1 .LBB0_1208
	v_bfe_u32 v2, v1, 5, 1
	v_and_b32_e32 v3, 31, v1
	s_lshl_b64 s[56:57], s[24:25], 20
	v_or_b32_e32 v193, s52, v3
	v_lshlrev_b32_e32 v194, 2, v2
	v_lshrrev_b32_e32 v4, 2, v1
	v_and_b32_e32 v16, 16, v1
	v_lshlrev_b32_e32 v1, 2, v1
	v_mul_u32_u24_e32 v18, 0xc8, v3
	v_lshlrev_b32_e32 v202, 4, v2
	v_lshl_add_u64 v[2:3], s[56:57], 0, v[172:173]
	s_ashr_i32 s11, s10, 31
	v_and_b32_e32 v17, 12, v1
	v_add_u32_e32 v1, v192, v191
	v_lshl_add_u64 v[2:3], v[170:171], 1, v[2:3]
	s_lshl_b64 s[56:57], s[10:11], 20
	v_mul_lo_u32 v5, v1, s37
	v_mul_lo_u32 v195, v1, s38
	v_mov_b32_e32 v1, s57
	v_subrev_co_u32_e32 v2, vcc, s56, v2
	v_lshrrev_b32_e32 v6, 31, v190
	s_nop 0
	v_subb_co_u32_e32 v3, vcc, v3, v1, vcc
	v_lshl_add_u64 v[174:175], s[16:17], 0, v[2:3]
	v_lshlrev_b64 v[2:3], 1, v[168:169]
	v_ashrrev_i32_e32 v7, 2, v190
	v_lshrrev_b32_e32 v8, 31, v189
	v_ashrrev_i32_e32 v9, 2, v189
	v_mad_i64_i32 v[2:3], s[56:57], s24, v181, v[2:3]
	v_add_u32_e32 v6, v7, v6
	v_add_u32_e32 v8, v9, v8
	v_mov_b32_e32 v1, s53
	v_subrev_co_u32_e32 v2, vcc, s54, v2
	v_and_or_b32 v4, v4, 3, v194
	v_mul_lo_u32 v7, v6, s37
	v_mul_lo_u32 v9, v8, s37
	v_subb_co_u32_e32 v3, vcc, v3, v1, vcc
	v_mov_b32_e32 v14, v0
	v_mov_b32_e32 v15, v0
	v_add_lshl_u32 v196, v5, v185, 4
	v_mul_lo_u32 v197, v6, s38
	v_add_lshl_u32 v198, v7, v188, 4
	v_mul_lo_u32 v199, v8, s38
	v_add_lshl_u32 v200, v9, v187, 4
	v_mul_u32_u24_e32 v201, 0x140, v4
	v_lshl_add_u64 v[176:177], s[20:21], 0, v[2:3]
	s_nop 0
	v_readfirstlane_b32 s88, v176
	v_readfirstlane_b32 s89, v177
	v_readfirstlane_b32 s94, v174
	v_readfirstlane_b32 s95, v175
	s_nop 3
	v_subrev_u32_e32 v252, s88, v176
	v_subrev_u32_e32 v253, s94, v174
	s_add_u32 s90, s88, 0x2000
	s_addc_u32 s91, s89, 0
	s_add_u32 s92, s88, 0x4000
	s_addc_u32 s93, s89, 0
	s_add_u32 s96, s94, 0x2000
	s_addc_u32 s97, s95, 0
	v_mov_b32_e32 v1, v0
	v_mov_b32_e32 v2, v0
	v_mov_b32_e32 v3, v0
	v_mov_b32_e32 v4, v0
	v_mov_b32_e32 v5, v0
	v_mov_b32_e32 v6, v0
	v_mov_b32_e32 v7, v0
	v_mov_b32_e32 v8, v0
	v_mov_b32_e32 v9, v0
	v_mov_b32_e32 v10, v0
	v_mov_b32_e32 v11, v0
	v_mov_b32_e32 v12, v0
	v_mov_b32_e32 v13, v0
	v_lshlrev_b32_e32 v203, 1, v18
	v_mov_b64_e32 v[48:49], v[14:15]
	v_mov_b64_e32 v[64:65], v[14:15]
	v_mov_b64_e32 v[32:33], v[14:15]
	v_lshlrev_b32_e32 v204, 1, v16
	v_lshlrev_b32_e32 v205, 1, v17
	v_mov_b64_e32 v[46:47], v[12:13]
	v_mov_b64_e32 v[44:45], v[10:11]
	v_mov_b64_e32 v[42:43], v[8:9]
	v_mov_b64_e32 v[40:41], v[6:7]
	v_mov_b64_e32 v[38:39], v[4:5]
	v_mov_b64_e32 v[36:37], v[2:3]
	v_mov_b64_e32 v[34:35], v[0:1]
	v_mov_b64_e32 v[62:63], v[12:13]
	v_mov_b64_e32 v[60:61], v[10:11]
	v_mov_b64_e32 v[58:59], v[8:9]
	v_mov_b64_e32 v[56:57], v[6:7]
	v_mov_b64_e32 v[54:55], v[4:5]
	v_mov_b64_e32 v[52:53], v[2:3]
	v_mov_b64_e32 v[50:51], v[0:1]
	v_mov_b64_e32 v[30:31], v[12:13]
	v_mov_b64_e32 v[28:29], v[10:11]
	v_mov_b64_e32 v[26:27], v[8:9]
	v_mov_b64_e32 v[24:25], v[6:7]
	v_mov_b64_e32 v[22:23], v[4:5]
	v_mov_b64_e32 v[20:21], v[2:3]
	v_mov_b64_e32 v[18:19], v[0:1]
	v_mov_b64_e32 v[16:17], v[14:15]
	s_mov_b32 s11, 0
	v_mov_b32_e32 v186, 0
	v_mov_b32_e32 v206, 0xf149f2ca
	v_mov_b32_e32 v232, 0
	v_mov_b32_e32 v233, 0
	v_mov_b32_e32 v234, 0
	v_mov_b32_e32 v235, 0
	v_mov_b32_e32 v236, 0
	v_mov_b32_e32 v237, 0
	v_mov_b32_e32 v238, 0
	v_mov_b32_e32 v239, 0
	v_mov_b32_e32 v240, 0
	v_mov_b32_e32 v241, 0
	v_mov_b32_e32 v242, 0
	v_mov_b32_e32 v243, 0
	v_mov_b32_e32 v244, 0
	v_mov_b32_e32 v245, 0
	v_mov_b32_e32 v246, 0
	v_mov_b32_e32 v247, 0
	v_mov_b32_e32 v248, 0
	v_mov_b32_e32 v249, v206
	s_mov_b32 s55, 63
	v_mov_b64_e32 v[14:15], v[12:13]
	v_mov_b64_e32 v[12:13], v[10:11]
	v_mov_b64_e32 v[10:11], v[8:9]
	v_mov_b64_e32 v[8:9], v[6:7]
	v_mov_b64_e32 v[6:7], v[4:5]
	v_mov_b64_e32 v[4:5], v[2:3]
	v_mov_b64_e32 v[2:3], v[0:1]
	s_branch .LBB0_1201
.LBB0_1200:
	v_exp_f32_e32 v207, v82
	v_exp_f32_e32 v208, v83
	v_exp_f32_e32 v209, v84
	v_add_u32_e32 v1, s56, v201
	v_exp_f32_e32 v211, v86
	v_add3_u32 v1, v1, v204, v205
	v_exp_f32_e32 v224, v88
	v_exp_f32_e32 v226, v87
	v_exp_f32_e32 v225, v89
	v_exp_f32_e32 v227, v85
	ds_read_b64_tr_b16 v[86:87], v1 offset:25600
	ds_read_b64_tr_b16 v[88:89], v1 offset:28160
	v_cvt_pk_bf16_f32 v84, v211, v226
	v_cvt_pk_bf16_f32 v85, v224, v225
	v_cvt_pk_bf16_f32 v83, v209, v227
	v_cvt_pk_bf16_f32 v82, v207, v208
	ds_read_b64_tr_b16 v[212:213], v1 offset:25664
	ds_read_b64_tr_b16 v[216:217], v1 offset:25728
	ds_read_b64_tr_b16 v[220:221], v1 offset:25792
	ds_read_b64_tr_b16 v[214:215], v1 offset:28224
	ds_read_b64_tr_b16 v[218:219], v1 offset:28288
	ds_read_b64_tr_b16 v[222:223], v1 offset:28352
	s_waitcnt lgkmcnt(6)
	v_mfma_f32_32x32x16_bf16 v[50:65], v[86:89], v[82:85], v[50:65]
	v_exp_f32_e32 v228, v90
	v_exp_f32_e32 v229, v91
	v_exp_f32_e32 v230, v92
	v_exp_f32_e32 v231, v94
	s_waitcnt lgkmcnt(1)
	v_mfma_f32_32x32x16_bf16 v[18:33], v[216:219], v[82:85], v[18:33]
	v_exp_f32_e32 v216, v96
	v_exp_f32_e32 v217, v97
	v_exp_f32_e32 v218, v95
	v_exp_f32_e32 v219, v93
	ds_read_b64_tr_b16 v[86:87], v1 offset:30720
	ds_read_b64_tr_b16 v[88:89], v1 offset:33280
	v_add_f32_e32 v207, 0, v207
	v_mfma_f32_32x32x16_bf16 v[34:49], v[212:215], v[82:85], v[34:49]
	ds_read_b64_tr_b16 v[90:91], v1 offset:30784
	ds_read_b64_tr_b16 v[94:95], v1 offset:30848
	ds_read_b64_tr_b16 v[212:213], v1 offset:30912
	ds_read_b64_tr_b16 v[92:93], v1 offset:33344
	ds_read_b64_tr_b16 v[96:97], v1 offset:33408
	ds_read_b64_tr_b16 v[214:215], v1 offset:33472
	s_add_i32 s55, s55, 64
	s_add_u32 s94, s94, s14
	s_addc_u32 s95, s95, s15
	s_add_u32 s96, s96, s14
	s_addc_u32 s97, s97, s15
	s_add_u32 s88, s88, s18
	s_addc_u32 s89, s89, s19
	s_add_u32 s90, s90, s18
	s_addc_u32 s91, s91, s19
	s_add_u32 s92, s92, s18
	s_addc_u32 s93, s93, s19
	s_cmp_eq_u32 s2, s11
	s_waitcnt lgkmcnt(8)
	v_mfma_f32_32x32x16_bf16 v[2:17], v[220:223], v[82:85], v[2:17]
	v_cvt_pk_bf16_f32 v85, v216, v217
	v_cvt_pk_bf16_f32 v84, v231, v218
	v_cvt_pk_bf16_f32 v83, v230, v219
	v_cvt_pk_bf16_f32 v82, v228, v229
	s_waitcnt lgkmcnt(6)
	s_nop 0
	v_mfma_f32_32x32x16_bf16 v[50:65], v[86:89], v[82:85], v[50:65]
	v_add_f32_e32 v86, v208, v207
	v_add_f32_e32 v86, v209, v86
	v_exp_f32_e32 v208, v66
	v_add_f32_e32 v86, v227, v86
	v_exp_f32_e32 v209, v67
	v_add_f32_e32 v86, v211, v86
	v_exp_f32_e32 v211, v68
	v_exp_f32_e32 v220, v70
	s_waitcnt lgkmcnt(1)
	v_mfma_f32_32x32x16_bf16 v[18:33], v[94:97], v[82:85], v[18:33]
	v_exp_f32_e32 v94, v72
	v_exp_f32_e32 v95, v73
	v_exp_f32_e32 v96, v71
	v_exp_f32_e32 v97, v69
	ds_read_b64_tr_b16 v[70:71], v1 offset:35840
	ds_read_b64_tr_b16 v[72:73], v1 offset:38400
	v_add_f32_e32 v207, v226, v86
	v_cvt_pk_bf16_f32 v69, v94, v95
	v_cvt_pk_bf16_f32 v68, v220, v96
	v_cvt_pk_bf16_f32 v67, v211, v97
	v_cvt_pk_bf16_f32 v66, v208, v209
	v_mfma_f32_32x32x16_bf16 v[34:49], v[90:93], v[82:85], v[34:49]
	s_waitcnt lgkmcnt(0)
	v_mfma_f32_32x32x16_bf16 v[50:65], v[70:73], v[66:69], v[50:65]
	v_add_f32_e32 v70, v224, v207
	v_add_f32_e32 v70, v225, v70
	v_add_f32_e32 v70, v228, v70
	v_add_f32_e32 v70, v229, v70
	v_add_f32_e32 v207, v230, v70
	v_mfma_f32_32x32x16_bf16 v[2:17], v[212:215], v[82:85], v[2:17]
	ds_read_b64_tr_b16 v[82:83], v1 offset:35904
	ds_read_b64_tr_b16 v[86:87], v1 offset:35968
	ds_read_b64_tr_b16 v[90:91], v1 offset:36032
	ds_read_b64_tr_b16 v[84:85], v1 offset:38464
	ds_read_b64_tr_b16 v[88:89], v1 offset:38528
	ds_read_b64_tr_b16 v[92:93], v1 offset:38592
	v_exp_f32_e32 v212, v74
	v_exp_f32_e32 v213, v75
	v_exp_f32_e32 v214, v76
	v_exp_f32_e32 v215, v78
	s_waitcnt lgkmcnt(1)
	v_mfma_f32_32x32x16_bf16 v[18:33], v[86:89], v[66:69], v[18:33]
	v_exp_f32_e32 v86, v80
	v_exp_f32_e32 v87, v81
	v_exp_f32_e32 v88, v79
	v_exp_f32_e32 v89, v77
	ds_read_b64_tr_b16 v[70:71], v1 offset:40960
	ds_read_b64_tr_b16 v[72:73], v1 offset:43520
	v_mfma_f32_32x32x16_bf16 v[34:49], v[82:85], v[66:69], v[34:49]
	ds_read_b64_tr_b16 v[74:75], v1 offset:41024
	ds_read_b64_tr_b16 v[78:79], v1 offset:41088
	ds_read_b64_tr_b16 v[82:83], v1 offset:41152
	ds_read_b64_tr_b16 v[76:77], v1 offset:43584
	ds_read_b64_tr_b16 v[80:81], v1 offset:43648
	ds_read_b64_tr_b16 v[84:85], v1 offset:43712
	v_add_f32_e32 v1, v219, v207
	v_add_f32_e32 v1, v231, v1
	v_add_f32_e32 v1, v218, v1
	v_add_f32_e32 v1, v216, v1
	v_add_f32_e32 v1, v217, v1
	v_add_f32_e32 v1, v208, v1
	s_waitcnt lgkmcnt(8)
	v_mfma_f32_32x32x16_bf16 v[2:17], v[90:93], v[66:69], v[2:17]
	v_add_f32_e32 v1, v209, v1
	v_add_f32_e32 v1, v211, v1
	v_add_f32_e32 v1, v97, v1
	v_add_f32_e32 v1, v220, v1
	v_add_f32_e32 v1, v96, v1
	v_add_f32_e32 v1, v94, v1
	v_add_f32_e32 v1, v95, v1
	v_cvt_pk_bf16_f32 v69, v86, v87
	v_cvt_pk_bf16_f32 v68, v215, v88
	v_cvt_pk_bf16_f32 v67, v214, v89
	v_cvt_pk_bf16_f32 v66, v212, v213
	v_add_f32_e32 v1, v212, v1
	v_add_f32_e32 v1, v213, v1
	s_waitcnt lgkmcnt(6)
	v_mfma_f32_32x32x16_bf16 v[50:65], v[70:73], v[66:69], v[50:65]
	v_add_f32_e32 v1, v214, v1
	v_add_f32_e32 v1, v89, v1
	v_add_f32_e32 v1, v215, v1
	v_add_f32_e32 v1, v88, v1
	v_add_f32_e32 v1, v86, v1
	v_add_f32_e32 v1, v87, v1
	v_add_f32_e32 v186, v186, v1
	s_waitcnt lgkmcnt(2)
	v_mfma_f32_32x32x16_bf16 v[34:49], v[74:77], v[66:69], v[34:49]
	s_waitcnt lgkmcnt(1)
	v_mfma_f32_32x32x16_bf16 v[18:33], v[78:81], v[66:69], v[18:33]
	s_waitcnt lgkmcnt(0)
	v_mfma_f32_32x32x16_bf16 v[2:17], v[82:85], v[66:69], v[2:17]
	s_cbranch_scc1 .LBB0_1207
.LBB0_1201:
	s_bitcmp1_b32 s11, 0
	s_cselect_b32 s56, 0xb400, 0
	v_add3_u32 v1, s56, v195, v196
	s_waitcnt vmcnt(4)
	ds_write_b128 v1, v[98:101]
	v_add3_u32 v1, s56, v197, v198
	s_waitcnt vmcnt(3)
	ds_write_b128 v1, v[102:105]
	v_add3_u32 v1, s56, v199, v200
	s_add_i32 s11, s11, 1
	s_waitcnt vmcnt(2)
	ds_write_b128 v1, v[106:109]
	v_add3_u32 v1, s56, v183, v184
	s_cmp_ge_i32 s11, s9
	s_waitcnt vmcnt(1)
	ds_write_b128 v1, v[110:113] offset:25600
	s_waitcnt vmcnt(0)
	ds_write_b128 v1, v[114:117] offset:35840
	s_cbranch_scc1 .LBB0_1203
	global_load_dwordx4 v[98:101], v252, s[88:89]
	global_load_dwordx4 v[102:105], v252, s[90:91]
	global_load_dwordx4 v[106:109], v252, s[92:93]
	global_load_dwordx4 v[110:113], v253, s[94:95]
	global_load_dwordx4 v[114:117], v253, s[96:97]
